# grid-barrier poll interval s_sleep 1 -> 3 plus K-loop no-op wait/setprio trim on the non-GEMM latency stack
# speedup vs baseline: 1.0034x; 1.0034x over previous
; __device__ __forceinline__ unsigned xb_ld(unsigned* p)              { return __hip_atomic_load(p, __ATOMIC_RELAXED, __HIP_MEMORY_SCOPE_AGENT); }
; __device__ __forceinline__ void xcd_barrier_complete(unsigned* bar, unsigned x, unsigned& nloc, unsigned& nx) {
;     const unsigned G = gridDim.x * gridDim.y * gridDim.z;
;     unsigned sum, cnt, mine, sp = 0u;
;     for (;;) {
;         sum = 0u; cnt = 0u; mine = 0u;
; #pragma unroll
;         for (unsigned j = 0; j < 16; ++j) { const unsigned c = xb_ld(&bar[XB_XCNT(j)]); sum += c; cnt += (c > 0u) ? 1u : 0u; mine = (j == x) ? c : mine; }
;         if (sum == G) break;
;         __builtin_amdgcn_s_sleep(1);
;         if ((++sp & 255u) == 0u) { if (xb_ld(&bar[XB_TMO])) break; if (sp > XB_SPIN_CAP) { atomicAdd(&bar[XB_TMO], 1u); break; } }
;     }
;     nloc = mine > 0u ? mine : 1u; nx = cnt > 0u ? cnt : 1u;
; }
.LBB0_506:
	global_load_dword v15, v235, s[4:5] sc1
	s_waitcnt lgkmcnt(0)
	global_load_dword v0, v235, s[6:7] sc1
	global_load_dword v1, v235, s[8:9] sc1
	global_load_dword v2, v235, s[10:11] sc1
	global_load_dword v3, v235, s[12:13] sc1
	global_load_dword v4, v235, s[14:15] sc1
	global_load_dword v5, v235, s[16:17] sc1
	global_load_dword v6, v235, s[18:19] sc1
	global_load_dword v7, v235, s[20:21] sc1
	global_load_dword v8, v235, s[22:23] sc1
	global_load_dword v9, v235, s[24:25] sc1
	global_load_dword v10, v235, s[26:27] sc1
	global_load_dword v11, v235, s[28:29] sc1
	global_load_dword v12, v235, s[30:31] sc1
	global_load_dword v13, v235, s[34:35] sc1
	global_load_dword v14, v235, s[36:37] sc1
	s_mov_b64 s[38:39], -1
	s_mov_b64 s[40:41], -1
	s_waitcnt vmcnt(14)
	v_add_u32_e32 v16, v0, v15
	s_waitcnt vmcnt(13)
	v_add_u32_e32 v16, v16, v1
	s_waitcnt vmcnt(12)
	v_add_u32_e32 v16, v16, v2
	s_waitcnt vmcnt(11)
	v_add_u32_e32 v16, v16, v3
	s_waitcnt vmcnt(10)
	v_add_u32_e32 v16, v16, v4
	s_waitcnt vmcnt(9)
	v_add_u32_e32 v16, v16, v5
	s_waitcnt vmcnt(8)
	v_add_u32_e32 v16, v16, v6
	s_waitcnt vmcnt(7)
	v_add_u32_e32 v16, v16, v7
	s_waitcnt vmcnt(6)
	v_add_u32_e32 v16, v16, v8
	s_waitcnt vmcnt(5)
	v_add_u32_e32 v16, v16, v9
	s_waitcnt vmcnt(4)
	v_add_u32_e32 v16, v16, v10
	s_waitcnt vmcnt(3)
	v_add_u32_e32 v16, v16, v11
	s_waitcnt vmcnt(2)
	v_add_u32_e32 v16, v16, v12
	s_waitcnt vmcnt(1)
	v_add_u32_e32 v16, v16, v13
	s_waitcnt vmcnt(0)
	v_add_u32_e32 v16, v16, v14
	v_cmp_eq_u32_e32 vcc, s52, v16
	s_cbranch_vccnz .LBB0_505
	s_and_b32 s33, s48, 0xff
	s_cmp_eq_u32 s33, 0
	s_mov_b64 s[46:47], -1
	s_sleep 3
	s_cbranch_scc1 .LBB0_510
	s_and_b64 vcc, exec, s[46:47]
	s_cbranch_vccz .LBB0_505

; __device__ __forceinline__ unsigned xb_ld(unsigned* p)              { return __hip_atomic_load(p, __ATOMIC_RELAXED, __HIP_MEMORY_SCOPE_AGENT); }
; #define XB_SPIN(cond, bar) do { unsigned _sp = 0; while (cond) { __builtin_amdgcn_s_sleep(1); \
;     if ((++_sp & 255u) == 0u) { if (xb_ld(&(bar)[XB_TMO])) break; if (_sp > XB_SPIN_CAP) { atomicAdd(&(bar)[XB_TMO], 1u); break; } } } } while (0)
; __device__ __forceinline__ void xcd_barrier(unsigned* bar, volatile LAS unsigned* st) {
;     ...
;             else XB_SPIN(xb_ld(&bar[XB_TOPGEN]) == tg, bar);
.LBB0_524:
	s_and_b32 s18, s22, 0xff
	s_mov_b64 s[16:17], -1
	s_cmp_lg_u32 s18, 0
	s_mov_b64 s[20:21], -1
	s_sleep 3
	s_cbranch_scc0 .LBB0_527
	s_and_b64 vcc, exec, s[20:21]
	s_cbranch_vccz .LBB0_523

; __device__ __forceinline__ unsigned xb_ld(unsigned* p)              { return __hip_atomic_load(p, __ATOMIC_RELAXED, __HIP_MEMORY_SCOPE_AGENT); }
; __device__ __forceinline__ void xcd_barrier_complete(unsigned* bar, unsigned x, unsigned& nloc, unsigned& nx) {
;     const unsigned G = gridDim.x * gridDim.y * gridDim.z;
;     unsigned sum, cnt, mine, sp = 0u;
;     for (;;) {
;         sum = 0u; cnt = 0u; mine = 0u;
; #pragma unroll
;         for (unsigned j = 0; j < 16; ++j) { const unsigned c = xb_ld(&bar[XB_XCNT(j)]); sum += c; cnt += (c > 0u) ? 1u : 0u; mine = (j == x) ? c : mine; }
;         if (sum == G) break;
;         __builtin_amdgcn_s_sleep(1);
;         if ((++sp & 255u) == 0u) { if (xb_ld(&bar[XB_TMO])) break; if (sp > XB_SPIN_CAP) { atomicAdd(&bar[XB_TMO], 1u); break; } }
;     }
;     nloc = mine > 0u ? mine : 1u; nx = cnt > 0u ? cnt : 1u;
; }
.LBB0_576:
	global_load_dword v16, v17, s[8:9] sc1
	s_waitcnt lgkmcnt(0)
	global_load_dword v1, v17, s[10:11] sc1
	global_load_dword v2, v17, s[12:13] sc1
	global_load_dword v3, v17, s[14:15] sc1
	global_load_dword v4, v17, s[16:17] sc1
	global_load_dword v5, v17, s[18:19] sc1
	global_load_dword v6, v17, s[20:21] sc1
	global_load_dword v7, v17, s[22:23] sc1
	global_load_dword v8, v17, s[24:25] sc1
	global_load_dword v9, v17, s[26:27] sc1
	global_load_dword v10, v17, s[28:29] sc1
	global_load_dword v11, v17, s[30:31] sc1
	global_load_dword v12, v17, s[34:35] sc1
	global_load_dword v13, v17, s[36:37] sc1
	global_load_dword v14, v17, s[38:39] sc1
	global_load_dword v15, v17, s[40:41] sc1
	s_mov_b64 s[42:43], -1
	s_mov_b64 s[44:45], -1
	s_waitcnt vmcnt(14)
	v_add_u32_e32 v18, v1, v16
	s_waitcnt vmcnt(13)
	v_add_u32_e32 v18, v18, v2
	s_waitcnt vmcnt(12)
	v_add_u32_e32 v18, v18, v3
	s_waitcnt vmcnt(11)
	v_add_u32_e32 v18, v18, v4
	s_waitcnt vmcnt(10)
	v_add_u32_e32 v18, v18, v5
	s_waitcnt vmcnt(9)
	v_add_u32_e32 v18, v18, v6
	s_waitcnt vmcnt(8)
	v_add_u32_e32 v18, v18, v7
	s_waitcnt vmcnt(7)
	v_add_u32_e32 v18, v18, v8
	s_waitcnt vmcnt(6)
	v_add_u32_e32 v18, v18, v9
	s_waitcnt vmcnt(5)
	v_add_u32_e32 v18, v18, v10
	s_waitcnt vmcnt(4)
	v_add_u32_e32 v18, v18, v11
	s_waitcnt vmcnt(3)
	v_add_u32_e32 v18, v18, v12
	s_waitcnt vmcnt(2)
	v_add_u32_e32 v18, v18, v13
	s_waitcnt vmcnt(1)
	v_add_u32_e32 v18, v18, v14
	s_waitcnt vmcnt(0)
	v_add_u32_e32 v18, v18, v15
	v_cmp_eq_u32_e32 vcc, s49, v18
	s_cbranch_vccnz .LBB0_575
	s_and_b32 s42, s50, 0xff
	s_cmp_eq_u32 s42, 0
	s_mov_b64 s[42:43], -1
	s_mov_b64 s[46:47], -1
	s_sleep 3
	s_cbranch_scc1 .LBB0_580
	s_and_b64 vcc, exec, s[46:47]
	s_cbranch_vccz .LBB0_575

; __device__ __forceinline__ unsigned xb_ld(unsigned* p)              { return __hip_atomic_load(p, __ATOMIC_RELAXED, __HIP_MEMORY_SCOPE_AGENT); }
; #define XB_SPIN(cond, bar) do { unsigned _sp = 0; while (cond) { __builtin_amdgcn_s_sleep(1); \
;     if ((++_sp & 255u) == 0u) { if (xb_ld(&(bar)[XB_TMO])) break; if (_sp > XB_SPIN_CAP) { atomicAdd(&(bar)[XB_TMO], 1u); break; } } } } while (0)
; __device__ __forceinline__ void xcd_barrier(unsigned* bar, volatile LAS unsigned* st) {
;     ...
;             else XB_SPIN(xb_ld(&bar[XB_TOPGEN]) == tg, bar);
.LBB0_594:
	s_and_b32 s22, s26, 0xff
	s_mov_b64 s[20:21], -1
	s_cmp_lg_u32 s22, 0
	s_mov_b64 s[24:25], -1
	s_sleep 3
	s_cbranch_scc0 .LBB0_597
	s_and_b64 vcc, exec, s[24:25]
	s_cbranch_vccz .LBB0_593

; __device__ __forceinline__ unsigned xb_ld(unsigned* p)              { return __hip_atomic_load(p, __ATOMIC_RELAXED, __HIP_MEMORY_SCOPE_AGENT); }
; #define XB_SPIN(cond, bar) do { unsigned _sp = 0; while (cond) { __builtin_amdgcn_s_sleep(1); \
;     if ((++_sp & 255u) == 0u) { if (xb_ld(&(bar)[XB_TMO])) break; if (_sp > XB_SPIN_CAP) { atomicAdd(&(bar)[XB_TMO], 1u); break; } } } } while (0)
; __device__ __forceinline__ void xcd_barrier(unsigned* bar, volatile LAS unsigned* st) {
;     ...
;             XB_SPIN(xb_ld(&bar[XB_XGEN(x)]) == gen, bar);
.LBB0_611:
	s_and_b32 s18, s24, 0xff
	s_cmp_lg_u32 s18, 0
	s_mov_b64 s[20:21], -1
	s_sleep 3
	s_cbranch_scc0 .LBB0_614
	s_mov_b64 s[22:23], -1
	s_and_b64 vcc, exec, s[20:21]
	s_cbranch_vccz .LBB0_610

; __global__ void __launch_bounds__(512, 2) __attribute__((amdgpu_waves_per_eu(2, 2))) mk_fwd(Args a_) {
;     ...
;         if (hi < 0) grid.sync();
.LBB0_633:
	s_sleep 3
	global_load_dword v2, v0, s[0:1] offset:32 sc1
	s_waitcnt vmcnt(0)
	v_and_b32_e32 v2, 0xffff0000, v2
	v_cmp_ne_u32_e32 vcc, v2, v1
	s_or_b64 s[4:5], vcc, s[4:5]
	s_andn2_b64 exec, exec, s[4:5]
	s_cbranch_execnz .LBB0_633
